# chunk-MLP items re-split 1/4 (P3) 0/5 (P5) with per-chunk LN statistics, on top of dwordx4 permlane16 stores
# baseline (speedup 1.0000x reference)
.Lcma_top:
	s_waitcnt vmcnt(4)
	s_and_b32 s0, s5, 7
	s_cmp_lg_u32 s0, 0
	s_cbranch_scc1 .Lcma_copy

.Lcma_pf1:
	global_load_dwordx4 v[100:103], v200, s[46:47]
	global_load_dwordx4 v[116:119], v204, s[48:49]
	global_load_dwordx4 v[104:107], v201, s[46:47]
	global_load_dwordx4 v[120:123], v205, s[48:49]
	global_load_dwordx4 v[108:111], v202, s[46:47]
	global_load_dwordx4 v[124:127], v206, s[48:49]
	global_load_dwordx4 v[112:115], v203, s[46:47]
	global_load_dwordx4 v[128:131], v207, s[48:49]
	global_load_dwordx4 v[164:167], v209, s[14:15]
	global_load_dwordx4 v[168:171], v209, s[16:17]
	global_load_dwordx4 v[172:175], v209, s[16:17] offset:16
	global_load_dwordx4 v[176:179], v209, s[14:15] offset:16
	global_load_dword v236, v210, s[10:11]
	global_load_dwordx2 v[220:221], v211, s[6:7]
	global_load_dwordx2 v[222:223], v211, s[6:7] offset:32
	global_load_dwordx2 v[224:225], v211, s[6:7] offset:64
	global_load_dwordx2 v[226:227], v211, s[6:7] offset:96
	global_load_dwordx2 v[228:229], v211, s[6:7] offset:128
	global_load_dwordx2 v[230:231], v211, s[6:7] offset:160
	global_load_dwordx2 v[232:233], v211, s[6:7] offset:192
	global_load_dwordx2 v[234:235], v211, s[6:7] offset:224
.Lcma_nopf:
	s_waitcnt lgkmcnt(0)
	s_barrier
	ds_read_b64 v[88:89], v214
	ds_read_b64 v[90:91], v214 offset:256
	ds_read_b64 v[92:93], v214 offset:512
	ds_read_b64 v[94:95], v214 offset:768
	s_waitcnt lgkmcnt(3)
	v_lshlrev_b32_e32 v56, 16, v0
	v_and_b32_e32 v57, 0xffff0000, v0
	v_lshlrev_b32_e32 v58, 16, v1
	v_and_b32_e32 v59, 0xffff0000, v1
	v_lshlrev_b32_e32 v60, 16, v2
	v_and_b32_e32 v61, 0xffff0000, v2
	v_lshlrev_b32_e32 v62, 16, v3
	v_and_b32_e32 v63, 0xffff0000, v3
	v_sub_f32_e32 v56, v56, v88
	v_sub_f32_e32 v57, v57, v88
	v_sub_f32_e32 v58, v58, v88
	v_sub_f32_e32 v59, v59, v88
	v_sub_f32_e32 v60, v60, v88
	v_sub_f32_e32 v61, v61, v88
	v_sub_f32_e32 v62, v62, v88
	v_sub_f32_e32 v63, v63, v88
	v_mul_f32_e32 v56, v89, v56
	v_mul_f32_e32 v57, v89, v57
	v_mul_f32_e32 v58, v89, v58
	v_mul_f32_e32 v59, v89, v59
	v_mul_f32_e32 v60, v89, v60
	v_mul_f32_e32 v61, v89, v61
	v_mul_f32_e32 v62, v89, v62
	v_mul_f32_e32 v63, v89, v63
	v_fma_f32 v56, v42, v56, v38
	v_fma_f32 v57, v43, v57, v39
	v_fma_f32 v58, v44, v58, v40
	v_fma_f32 v59, v45, v59, v41
	v_fma_f32 v60, v46, v60, v50
	v_fma_f32 v61, v47, v61, v51
	v_fma_f32 v62, v48, v62, v52
	v_fma_f32 v63, v49, v63, v53
	v_cvt_pk_bf16_f32 v64, v56, v57
	v_cvt_pk_bf16_f32 v65, v58, v59
	v_cvt_pk_bf16_f32 v66, v60, v61
	v_cvt_pk_bf16_f32 v67, v62, v63
	ds_write_b128 v212, v[64:67]
	ds_write_b128 v213, v[16:19]
	s_waitcnt lgkmcnt(4)
	v_lshlrev_b32_e32 v56, 16, v4
	v_and_b32_e32 v57, 0xffff0000, v4
	v_lshlrev_b32_e32 v58, 16, v5
	v_and_b32_e32 v59, 0xffff0000, v5
	v_lshlrev_b32_e32 v60, 16, v6
	v_and_b32_e32 v61, 0xffff0000, v6
	v_lshlrev_b32_e32 v62, 16, v7
	v_and_b32_e32 v63, 0xffff0000, v7
	v_sub_f32_e32 v56, v56, v90
	v_sub_f32_e32 v57, v57, v90
	v_sub_f32_e32 v58, v58, v90
	v_sub_f32_e32 v59, v59, v90
	v_sub_f32_e32 v60, v60, v90
	v_sub_f32_e32 v61, v61, v90
	v_sub_f32_e32 v62, v62, v90
	v_sub_f32_e32 v63, v63, v90
	v_mul_f32_e32 v56, v91, v56
	v_mul_f32_e32 v57, v91, v57
	v_mul_f32_e32 v58, v91, v58
	v_mul_f32_e32 v59, v91, v59
	v_mul_f32_e32 v60, v91, v60
	v_mul_f32_e32 v61, v91, v61
	v_mul_f32_e32 v62, v91, v62
	v_mul_f32_e32 v63, v91, v63
	v_fma_f32 v56, v42, v56, v38
	v_fma_f32 v57, v43, v57, v39
	v_fma_f32 v58, v44, v58, v40
	v_fma_f32 v59, v45, v59, v41
	v_fma_f32 v60, v46, v60, v50
	v_fma_f32 v61, v47, v61, v51
	v_fma_f32 v62, v48, v62, v52
	v_fma_f32 v63, v49, v63, v53
	v_cvt_pk_bf16_f32 v64, v56, v57
	v_cvt_pk_bf16_f32 v65, v58, v59
	v_cvt_pk_bf16_f32 v66, v60, v61
	v_cvt_pk_bf16_f32 v67, v62, v63
	ds_write_b128 v212, v[64:67] offset:9216
	ds_write_b128 v213, v[20:23] offset:8704
	s_waitcnt lgkmcnt(5)
	v_lshlrev_b32_e32 v56, 16, v8
	v_and_b32_e32 v57, 0xffff0000, v8
	v_lshlrev_b32_e32 v58, 16, v9
	v_and_b32_e32 v59, 0xffff0000, v9
	v_lshlrev_b32_e32 v60, 16, v10
	v_and_b32_e32 v61, 0xffff0000, v10
	v_lshlrev_b32_e32 v62, 16, v11
	v_and_b32_e32 v63, 0xffff0000, v11
	v_sub_f32_e32 v56, v56, v92
	v_sub_f32_e32 v57, v57, v92
	v_sub_f32_e32 v58, v58, v92
	v_sub_f32_e32 v59, v59, v92
	v_sub_f32_e32 v60, v60, v92
	v_sub_f32_e32 v61, v61, v92
	v_sub_f32_e32 v62, v62, v92
	v_sub_f32_e32 v63, v63, v92
	v_mul_f32_e32 v56, v93, v56
	v_mul_f32_e32 v57, v93, v57
	v_mul_f32_e32 v58, v93, v58
	v_mul_f32_e32 v59, v93, v59
	v_mul_f32_e32 v60, v93, v60
	v_mul_f32_e32 v61, v93, v61
	v_mul_f32_e32 v62, v93, v62
	v_mul_f32_e32 v63, v93, v63
	v_fma_f32 v56, v42, v56, v38
	v_fma_f32 v57, v43, v57, v39
	v_fma_f32 v58, v44, v58, v40
	v_fma_f32 v59, v45, v59, v41
	v_fma_f32 v60, v46, v60, v50
	v_fma_f32 v61, v47, v61, v51
	v_fma_f32 v62, v48, v62, v52
	v_fma_f32 v63, v49, v63, v53
	v_cvt_pk_bf16_f32 v64, v56, v57
	v_cvt_pk_bf16_f32 v65, v58, v59
	v_cvt_pk_bf16_f32 v66, v60, v61
	v_cvt_pk_bf16_f32 v67, v62, v63
	ds_write_b128 v212, v[64:67] offset:18432
	ds_write_b128 v213, v[24:27] offset:17408
	s_waitcnt lgkmcnt(6)
	v_lshlrev_b32_e32 v56, 16, v12
	v_and_b32_e32 v57, 0xffff0000, v12
	v_lshlrev_b32_e32 v58, 16, v13
	v_and_b32_e32 v59, 0xffff0000, v13
	v_lshlrev_b32_e32 v60, 16, v14
	v_and_b32_e32 v61, 0xffff0000, v14
	v_lshlrev_b32_e32 v62, 16, v15
	v_and_b32_e32 v63, 0xffff0000, v15
	v_sub_f32_e32 v56, v56, v94
	v_sub_f32_e32 v57, v57, v94
	v_sub_f32_e32 v58, v58, v94
	v_sub_f32_e32 v59, v59, v94
	v_sub_f32_e32 v60, v60, v94
	v_sub_f32_e32 v61, v61, v94
	v_sub_f32_e32 v62, v62, v94
	v_sub_f32_e32 v63, v63, v94
	v_mul_f32_e32 v56, v95, v56
	v_mul_f32_e32 v57, v95, v57
	v_mul_f32_e32 v58, v95, v58
	v_mul_f32_e32 v59, v95, v59
	v_mul_f32_e32 v60, v95, v60
	v_mul_f32_e32 v61, v95, v61
	v_mul_f32_e32 v62, v95, v62
	v_mul_f32_e32 v63, v95, v63
	v_fma_f32 v56, v42, v56, v38
	v_fma_f32 v57, v43, v57, v39
	v_fma_f32 v58, v44, v58, v40
	v_fma_f32 v59, v45, v59, v41
	v_fma_f32 v60, v46, v60, v50
	v_fma_f32 v61, v47, v61, v51
	v_fma_f32 v62, v48, v62, v52
	v_fma_f32 v63, v49, v63, v53
	v_cvt_pk_bf16_f32 v64, v56, v57
	v_cvt_pk_bf16_f32 v65, v58, v59
	v_cvt_pk_bf16_f32 v66, v60, v61
	v_cvt_pk_bf16_f32 v67, v62, v63
	ds_write_b128 v212, v[64:67] offset:27648
	ds_write_b128 v213, v[28:31] offset:26112
	s_waitcnt lgkmcnt(0)
	s_barrier
	ds_read2_b64 v[12:15], v217 offset1:4
	ds_read2_b64 v[8:11], v217 offset0:8 offset1:12
	ds_read2_b64 v[0:3], v217 offset0:16 offset1:20
	ds_read2_b64 v[4:7], v217 offset0:24 offset1:28
	ds_read_b64_tr_b16 v[18:19], v216
	ds_read_b64_tr_b16 v[20:21], v216 offset:4608
	ds_read_b64_tr_b16 v[22:23], v216 offset:9216
	ds_read_b64_tr_b16 v[24:25], v216 offset:13824
	ds_read_b64_tr_b16 v[26:27], v216 offset:18432
	ds_read_b64_tr_b16 v[28:29], v216 offset:23040
	ds_read_b64_tr_b16 v[30:31], v216 offset:27648
	ds_read_b64_tr_b16 v[32:33], v216 offset:32256
	s_waitcnt lgkmcnt(0)
	ds_read_b64_tr_b16 v[54:55], v216 offset:32
	ds_read_b64_tr_b16 v[56:57], v216 offset:4640
	ds_read_b64_tr_b16 v[58:59], v216 offset:9248
	ds_read_b64_tr_b16 v[60:61], v216 offset:13856
	ds_read_b64_tr_b16 v[62:63], v216 offset:18464
	ds_read_b64_tr_b16 v[64:65], v216 offset:23072
	ds_read_b64_tr_b16 v[66:67], v216 offset:27680
	ds_read_b64_tr_b16 v[68:69], v216 offset:32288
	v_mfma_f32_16x16x32_bf16 v[34:37], v[18:21], v[12:15], 0
	v_mfma_f32_16x16x32_bf16 v[34:37], v[22:25], v[8:11], v[34:37]
	v_mfma_f32_16x16x32_bf16 v[34:37], v[26:29], v[0:3], v[34:37]
	v_mfma_f32_16x16x32_bf16 v[34:37], v[30:33], v[4:7], v[34:37]
	s_waitcnt lgkmcnt(0)
	ds_read_b64_tr_b16 v[18:19], v216 offset:64
	ds_read_b64_tr_b16 v[20:21], v216 offset:4672
	ds_read_b64_tr_b16 v[22:23], v216 offset:9280
	ds_read_b64_tr_b16 v[24:25], v216 offset:13888
	ds_read_b64_tr_b16 v[26:27], v216 offset:18496
	ds_read_b64_tr_b16 v[28:29], v216 offset:23104
	ds_read_b64_tr_b16 v[30:31], v216 offset:27712
	ds_read_b64_tr_b16 v[32:33], v216 offset:32320
	v_mfma_f32_16x16x32_bf16 v[88:91], v[54:57], v[12:15], 0
	v_lshlrev_b32_e32 v38, 16, v70
	v_and_b32_e32 v39, 0xffff0000, v70
	v_lshlrev_b32_e32 v40, 16, v71
	v_and_b32_e32 v41, 0xffff0000, v71
	v_mfma_f32_16x16x32_bf16 v[88:91], v[58:61], v[8:11], v[88:91]
	v_add_f32_e32 v42, v86, v34
	v_add_f32_e32 v43, v86, v35
	v_add_f32_e32 v44, v86, v36
	v_add_f32_e32 v45, v86, v37
	v_mfma_f32_16x16x32_bf16 v[88:91], v[62:65], v[0:3], v[88:91]
	v_mul_f32_e32 v42, v42, v38
	v_mul_f32_e32 v43, v43, v39
	v_mul_f32_e32 v44, v44, v40
	v_mul_f32_e32 v45, v45, v41
	v_mfma_f32_16x16x32_bf16 v[88:91], v[66:69], v[4:7], v[88:91]
	v_cvt_pk_bf16_f32 v48, v42, v43
	v_cvt_pk_bf16_f32 v49, v44, v45
	s_waitcnt lgkmcnt(0)
	ds_read_b64_tr_b16 v[54:55], v216 offset:96
	ds_read_b64_tr_b16 v[56:57], v216 offset:4704
	ds_read_b64_tr_b16 v[58:59], v216 offset:9312
	ds_read_b64_tr_b16 v[60:61], v216 offset:13920
	ds_read_b64_tr_b16 v[62:63], v216 offset:18528
	ds_read_b64_tr_b16 v[64:65], v216 offset:23136
	ds_read_b64_tr_b16 v[66:67], v216 offset:27744
	ds_read_b64_tr_b16 v[68:69], v216 offset:32352
	v_mfma_f32_16x16x32_bf16 v[34:37], v[18:21], v[12:15], 0
	v_lshlrev_b32_e32 v38, 16, v72
	v_and_b32_e32 v39, 0xffff0000, v72
	v_lshlrev_b32_e32 v40, 16, v73
	v_and_b32_e32 v41, 0xffff0000, v73
	v_mfma_f32_16x16x32_bf16 v[34:37], v[22:25], v[8:11], v[34:37]
	v_add_f32_e32 v42, v86, v88
	v_add_f32_e32 v43, v86, v89
	v_add_f32_e32 v44, v86, v90
	v_add_f32_e32 v45, v86, v91
	v_mfma_f32_16x16x32_bf16 v[34:37], v[26:29], v[0:3], v[34:37]
	v_mul_f32_e32 v42, v42, v38
	v_mul_f32_e32 v43, v43, v39
	v_mul_f32_e32 v44, v44, v40
	v_mul_f32_e32 v45, v45, v41
	v_mfma_f32_16x16x32_bf16 v[34:37], v[30:33], v[4:7], v[34:37]
	v_cvt_pk_bf16_f32 v50, v42, v43
	v_cvt_pk_bf16_f32 v51, v44, v45
	s_nop 1
	v_permlane16_swap_b32 v48, v50
	v_permlane16_swap_b32 v49, v51
	global_store_dwordx4 v218, v[48:51], s[12:13]
	s_waitcnt lgkmcnt(0)
	ds_read_b64_tr_b16 v[18:19], v216 offset:128
	ds_read_b64_tr_b16 v[20:21], v216 offset:4736
	ds_read_b64_tr_b16 v[22:23], v216 offset:9344
	ds_read_b64_tr_b16 v[24:25], v216 offset:13952
	ds_read_b64_tr_b16 v[26:27], v216 offset:18560
	ds_read_b64_tr_b16 v[28:29], v216 offset:23168
	ds_read_b64_tr_b16 v[30:31], v216 offset:27776
	ds_read_b64_tr_b16 v[32:33], v216 offset:32384
	v_mfma_f32_16x16x32_bf16 v[88:91], v[54:57], v[12:15], 0
	v_lshlrev_b32_e32 v38, 16, v74
	v_and_b32_e32 v39, 0xffff0000, v74
	v_lshlrev_b32_e32 v40, 16, v75
	v_and_b32_e32 v41, 0xffff0000, v75
	v_mfma_f32_16x16x32_bf16 v[88:91], v[58:61], v[8:11], v[88:91]
	v_add_f32_e32 v42, v86, v34
	v_add_f32_e32 v43, v86, v35
	v_add_f32_e32 v44, v86, v36
	v_add_f32_e32 v45, v86, v37
	v_mfma_f32_16x16x32_bf16 v[88:91], v[62:65], v[0:3], v[88:91]
	v_mul_f32_e32 v42, v42, v38
	v_mul_f32_e32 v43, v43, v39
	v_mul_f32_e32 v44, v44, v40
	v_mul_f32_e32 v45, v45, v41
	v_mfma_f32_16x16x32_bf16 v[88:91], v[66:69], v[4:7], v[88:91]
	v_cvt_pk_bf16_f32 v48, v42, v43
	v_cvt_pk_bf16_f32 v49, v44, v45
	s_waitcnt lgkmcnt(0)
	ds_read_b64_tr_b16 v[54:55], v216 offset:160
	ds_read_b64_tr_b16 v[56:57], v216 offset:4768
	ds_read_b64_tr_b16 v[58:59], v216 offset:9376
	ds_read_b64_tr_b16 v[60:61], v216 offset:13984
	ds_read_b64_tr_b16 v[62:63], v216 offset:18592
	ds_read_b64_tr_b16 v[64:65], v216 offset:23200
	ds_read_b64_tr_b16 v[66:67], v216 offset:27808
	ds_read_b64_tr_b16 v[68:69], v216 offset:32416
	v_mfma_f32_16x16x32_bf16 v[34:37], v[18:21], v[12:15], 0
	v_lshlrev_b32_e32 v38, 16, v76
	v_and_b32_e32 v39, 0xffff0000, v76
	v_lshlrev_b32_e32 v40, 16, v77
	v_and_b32_e32 v41, 0xffff0000, v77
	v_mfma_f32_16x16x32_bf16 v[34:37], v[22:25], v[8:11], v[34:37]
	v_add_f32_e32 v42, v86, v88
	v_add_f32_e32 v43, v86, v89
	v_add_f32_e32 v44, v86, v90
	v_add_f32_e32 v45, v86, v91
	v_mfma_f32_16x16x32_bf16 v[34:37], v[26:29], v[0:3], v[34:37]
	v_mul_f32_e32 v42, v42, v38
	v_mul_f32_e32 v43, v43, v39
	v_mul_f32_e32 v44, v44, v40
	v_mul_f32_e32 v45, v45, v41
	v_mfma_f32_16x16x32_bf16 v[34:37], v[30:33], v[4:7], v[34:37]
	v_cvt_pk_bf16_f32 v50, v42, v43
	v_cvt_pk_bf16_f32 v51, v44, v45
	s_nop 1
	v_permlane16_swap_b32 v48, v50
	v_permlane16_swap_b32 v49, v51
	global_store_dwordx4 v218, v[48:51], s[12:13] offset:64
	s_waitcnt lgkmcnt(0)
	ds_read_b64_tr_b16 v[18:19], v216 offset:192
	ds_read_b64_tr_b16 v[20:21], v216 offset:4800
	ds_read_b64_tr_b16 v[22:23], v216 offset:9408
	ds_read_b64_tr_b16 v[24:25], v216 offset:14016
	ds_read_b64_tr_b16 v[26:27], v216 offset:18624
	ds_read_b64_tr_b16 v[28:29], v216 offset:23232
	ds_read_b64_tr_b16 v[30:31], v216 offset:27840
	ds_read_b64_tr_b16 v[32:33], v216 offset:32448
	v_mfma_f32_16x16x32_bf16 v[88:91], v[54:57], v[12:15], 0
	v_lshlrev_b32_e32 v38, 16, v78
	v_and_b32_e32 v39, 0xffff0000, v78
	v_lshlrev_b32_e32 v40, 16, v79
	v_and_b32_e32 v41, 0xffff0000, v79
	v_mfma_f32_16x16x32_bf16 v[88:91], v[58:61], v[8:11], v[88:91]
	v_add_f32_e32 v42, v86, v34
	v_add_f32_e32 v43, v86, v35
	v_add_f32_e32 v44, v86, v36
	v_add_f32_e32 v45, v86, v37
	v_mfma_f32_16x16x32_bf16 v[88:91], v[62:65], v[0:3], v[88:91]
	v_mul_f32_e32 v42, v42, v38
	v_mul_f32_e32 v43, v43, v39
	v_mul_f32_e32 v44, v44, v40
	v_mul_f32_e32 v45, v45, v41
	v_mfma_f32_16x16x32_bf16 v[88:91], v[66:69], v[4:7], v[88:91]
	v_cvt_pk_bf16_f32 v48, v42, v43
	v_cvt_pk_bf16_f32 v49, v44, v45
	s_waitcnt lgkmcnt(0)
	ds_read_b64_tr_b16 v[54:55], v216 offset:224
	ds_read_b64_tr_b16 v[56:57], v216 offset:4832
	ds_read_b64_tr_b16 v[58:59], v216 offset:9440
	ds_read_b64_tr_b16 v[60:61], v216 offset:14048
	ds_read_b64_tr_b16 v[62:63], v216 offset:18656
	ds_read_b64_tr_b16 v[64:65], v216 offset:23264
	ds_read_b64_tr_b16 v[66:67], v216 offset:27872
	ds_read_b64_tr_b16 v[68:69], v216 offset:32480
	v_mfma_f32_16x16x32_bf16 v[34:37], v[18:21], v[12:15], 0
	v_lshlrev_b32_e32 v38, 16, v80
	v_and_b32_e32 v39, 0xffff0000, v80
	v_lshlrev_b32_e32 v40, 16, v81
	v_and_b32_e32 v41, 0xffff0000, v81
	v_mfma_f32_16x16x32_bf16 v[34:37], v[22:25], v[8:11], v[34:37]
	v_add_f32_e32 v42, v86, v88
	v_add_f32_e32 v43, v86, v89
	v_add_f32_e32 v44, v86, v90
	v_add_f32_e32 v45, v86, v91
	v_mfma_f32_16x16x32_bf16 v[34:37], v[26:29], v[0:3], v[34:37]
	v_mul_f32_e32 v42, v42, v38
	v_mul_f32_e32 v43, v43, v39
	v_mul_f32_e32 v44, v44, v40
	v_mul_f32_e32 v45, v45, v41
	v_mfma_f32_16x16x32_bf16 v[34:37], v[30:33], v[4:7], v[34:37]
	v_cvt_pk_bf16_f32 v50, v42, v43
	v_cvt_pk_bf16_f32 v51, v44, v45
	s_nop 1
	v_permlane16_swap_b32 v48, v50
	v_permlane16_swap_b32 v49, v51
	global_store_dwordx4 v218, v[48:51], s[12:13] offset:128
	s_waitcnt lgkmcnt(0)
	v_mfma_f32_16x16x32_bf16 v[88:91], v[54:57], v[12:15], 0
	v_lshlrev_b32_e32 v38, 16, v82
	v_and_b32_e32 v39, 0xffff0000, v82
	v_lshlrev_b32_e32 v40, 16, v83
	v_and_b32_e32 v41, 0xffff0000, v83
	v_mfma_f32_16x16x32_bf16 v[88:91], v[58:61], v[8:11], v[88:91]
	v_add_f32_e32 v42, v86, v34
	v_add_f32_e32 v43, v86, v35
	v_add_f32_e32 v44, v86, v36
	v_add_f32_e32 v45, v86, v37
	v_mfma_f32_16x16x32_bf16 v[88:91], v[62:65], v[0:3], v[88:91]
	v_mul_f32_e32 v42, v42, v38
	v_mul_f32_e32 v43, v43, v39
	v_mul_f32_e32 v44, v44, v40
	v_mul_f32_e32 v45, v45, v41
	v_mfma_f32_16x16x32_bf16 v[88:91], v[66:69], v[4:7], v[88:91]
	v_cvt_pk_bf16_f32 v48, v42, v43
	v_cvt_pk_bf16_f32 v49, v44, v45
	v_lshlrev_b32_e32 v38, 16, v84
	v_and_b32_e32 v39, 0xffff0000, v84
	v_lshlrev_b32_e32 v40, 16, v85
	v_and_b32_e32 v41, 0xffff0000, v85
	s_nop 3
	v_add_f32_e32 v42, v86, v88
	v_add_f32_e32 v43, v86, v89
	v_add_f32_e32 v44, v86, v90
	v_add_f32_e32 v45, v86, v91
	v_mul_f32_e32 v42, v42, v38
	v_mul_f32_e32 v43, v43, v39
	v_mul_f32_e32 v44, v44, v40
	v_mul_f32_e32 v45, v45, v41
	v_cvt_pk_bf16_f32 v50, v42, v43
	v_cvt_pk_bf16_f32 v51, v44, v45
	s_nop 1
	v_permlane16_swap_b32 v48, v50
	v_permlane16_swap_b32 v49, v51
	global_store_dwordx4 v218, v[48:51], s[12:13] offset:192
	s_add_i32 s5, s5, 1
	s_add_i32 s3, s3, -1
	s_cmp_gt_u32 s3, 0
	s_cbranch_scc1 .Lcma_top

.LBB0_890:
	v_readlane_b32 s4, v254, 39
	s_cmpk_lt_u32 s2, 0x80
	v_readlane_b32 s5, v254, 40
	s_cselect_b64 s[0:1], -1, 0
	s_xor_b64 s[4:5], s[4:5], -1
	s_or_b64 s[0:1], s[0:1], s[4:5]
	s_movk_i32 s3, 0x80
	s_and_b64 vcc, exec, s[0:1]
	s_cbranch_vccnz .LBB0_895
	s_cmpk_lt_i32 s2, 0x80
	s_cbranch_scc1 .LBB0_895
	s_mul_i32 s5, s2, 5
	s_add_i32 s5, s5, 0
	s_mov_b32 s3, 5
	s_add_u32 s8, s30, 0x800000
	s_addc_u32 s9, s31, 0
	s_mov_b32 s4, 0x3a800000
	v_readlane_b32 s36, v254, 21
	v_readlane_b32 s37, v254, 22
	v_readlane_b32 s38, v254, 19
	v_readlane_b32 s39, v254, 20
	v_readlane_b32 s40, v254, 25
	v_readlane_b32 s41, v254, 26
	v_readlane_b32 s42, v254, 41
	v_readlane_b32 s43, v254, 42
	v_readlane_b32 s44, v254, 43
	v_readlane_b32 s45, v254, 44
	v_readlane_b32 s96, v254, 45
	v_readlane_b32 s97, v254, 46
	v_and_b32_e32 v1, 15, v195
	v_lshrrev_b32_e32 v0, 4, v195
	v_lshlrev_b32_e32 v2, 4, v1
	v_lshl_add_u32 v200, v0, 11, v2
	v_add_u32_e32 v201, 0x10000, v200
	v_add_u32_e32 v202, 0x20000, v200
	v_add_u32_e32 v203, 0x30000, v200
	v_lshl_add_u32 v204, v0, 8, v2
	v_add_u32_e32 v205, 0x2000, v204
	v_add_u32_e32 v206, 0x4000, v204
	v_add_u32_e32 v207, 0x6000, v204
	v_and_b32_e32 v3, 0x7f, v195
	v_lshlrev_b32_e32 v208, 7, v3
	v_lshlrev_b32_e32 v209, 5, v1
	v_lshrrev_b32_e32 v4, 6, v195
	v_lshl_add_u32 v5, v4, 4, v1
	v_lshlrev_b32_e32 v210, 2, v5
	v_bfe_u32 v6, v195, 4, 2
	v_lshlrev_b32_e32 v7, 3, v6
	v_lshl_add_u32 v211, v5, 11, v7
	v_and_b32_e32 v219, 1, v6
	v_mul_u32_u24_e32 v219, 24, v219
	v_add_u32_e32 v218, v211, v219
	v_mul_u32_u24_e32 v8, 0x120, v0
	v_add_u32_e32 v212, v8, v2
	v_mul_u32_u24_e32 v8, 0x110, v0
	v_add_u32_e32 v8, v8, v2
	v_add_u32_e32 v213, 0x9000, v8
	v_lshlrev_b32_e32 v8, 3, v0
	v_add_u32_e32 v214, 0x11800, v8
	v_lshlrev_b32_e32 v8, 3, v195
	v_add_u32_e32 v215, 0x11800, v8
	v_lshrrev_b32_e32 v8, 2, v1
	v_lshl_or_b32 v8, v6, 2, v8
	v_mul_u32_u24_e32 v8, 0x120, v8
	v_and_b32_e32 v9, 3, v195
	v_lshl_add_u32 v216, v9, 3, v8
	v_mul_u32_u24_e32 v8, 0x110, v5
	v_add_u32_e32 v8, v8, v7
	v_add_u32_e32 v217, 0x9000, v8
	s_mov_b32 s0, s5
	s_and_b32 s1, s0, 7
	s_lshr_b32 s0, s0, 3
	s_lshl_b32 s0, s0, 7
	s_lshl_b32 s10, s1, 8
	s_lshl_b32 s11, s0, 11
	s_add_u32 s11, s11, s10
	s_add_u32 s46, s42, s11
	s_addc_u32 s47, s43, 0
	s_add_u32 s6, s96, s11
	s_addc_u32 s7, s97, 0
	s_lshl_b32 s10, s1, 15
	s_add_u32 s48, s8, s10
	s_addc_u32 s49, s9, 0
	s_lshl_b32 s10, s0, 7
	s_add_u32 s50, s44, s10
	s_addc_u32 s51, s45, 0
	s_lshl_b32 s10, s1, 9
	s_add_u32 s14, s36, s10
	s_addc_u32 s15, s37, 0
	s_add_u32 s16, s38, s10
	s_addc_u32 s17, s39, 0
	s_add_u32 s10, s40, s10
	s_addc_u32 s11, s41, 0
	v_readfirstlane_b32 s0, v195
	s_nop 1
	s_cmp_lt_u32 s0, 0x80
	s_cbranch_scc0 .Lcmb_pf0
	global_load_dwordx4 v[132:135], v208, s[50:51]
	global_load_dwordx4 v[136:139], v208, s[50:51] offset:16
	global_load_dwordx4 v[140:143], v208, s[50:51] offset:32
	global_load_dwordx4 v[144:147], v208, s[50:51] offset:48
	global_load_dwordx4 v[148:151], v208, s[50:51] offset:64
	global_load_dwordx4 v[152:155], v208, s[50:51] offset:80
	global_load_dwordx4 v[156:159], v208, s[50:51] offset:96
	global_load_dwordx4 v[160:163], v208, s[50:51] offset:112

.Lcmb_pf1:
	global_load_dwordx4 v[100:103], v200, s[46:47]
	global_load_dwordx4 v[116:119], v204, s[48:49]
	global_load_dwordx4 v[104:107], v201, s[46:47]
	global_load_dwordx4 v[120:123], v205, s[48:49]
	global_load_dwordx4 v[108:111], v202, s[46:47]
	global_load_dwordx4 v[124:127], v206, s[48:49]
	global_load_dwordx4 v[112:115], v203, s[46:47]
	global_load_dwordx4 v[128:131], v207, s[48:49]
	global_load_dwordx4 v[164:167], v209, s[14:15]
	global_load_dwordx4 v[168:171], v209, s[16:17]
	global_load_dwordx4 v[172:175], v209, s[16:17] offset:16
	global_load_dwordx4 v[176:179], v209, s[14:15] offset:16
	global_load_dword v236, v210, s[10:11]
	global_load_dwordx2 v[220:221], v211, s[6:7]
	global_load_dwordx2 v[222:223], v211, s[6:7] offset:32
	global_load_dwordx2 v[224:225], v211, s[6:7] offset:64
	global_load_dwordx2 v[226:227], v211, s[6:7] offset:96
	global_load_dwordx2 v[228:229], v211, s[6:7] offset:128
	global_load_dwordx2 v[230:231], v211, s[6:7] offset:160
	global_load_dwordx2 v[232:233], v211, s[6:7] offset:192
	global_load_dwordx2 v[234:235], v211, s[6:7] offset:224
.Lcmb_nopf:
	s_waitcnt lgkmcnt(0)
	s_barrier
	ds_read_b64 v[88:89], v214
	ds_read_b64 v[90:91], v214 offset:256
	ds_read_b64 v[92:93], v214 offset:512
	ds_read_b64 v[94:95], v214 offset:768
	s_waitcnt lgkmcnt(3)
	v_lshlrev_b32_e32 v56, 16, v0
	v_and_b32_e32 v57, 0xffff0000, v0
	v_lshlrev_b32_e32 v58, 16, v1
	v_and_b32_e32 v59, 0xffff0000, v1
	v_lshlrev_b32_e32 v60, 16, v2
	v_and_b32_e32 v61, 0xffff0000, v2
	v_lshlrev_b32_e32 v62, 16, v3
	v_and_b32_e32 v63, 0xffff0000, v3
	v_sub_f32_e32 v56, v56, v88
	v_sub_f32_e32 v57, v57, v88
	v_sub_f32_e32 v58, v58, v88
	v_sub_f32_e32 v59, v59, v88
	v_sub_f32_e32 v60, v60, v88
	v_sub_f32_e32 v61, v61, v88
	v_sub_f32_e32 v62, v62, v88
	v_sub_f32_e32 v63, v63, v88
	v_mul_f32_e32 v56, v89, v56
	v_mul_f32_e32 v57, v89, v57
	v_mul_f32_e32 v58, v89, v58
	v_mul_f32_e32 v59, v89, v59
	v_mul_f32_e32 v60, v89, v60
	v_mul_f32_e32 v61, v89, v61
	v_mul_f32_e32 v62, v89, v62
	v_mul_f32_e32 v63, v89, v63
	v_fma_f32 v56, v42, v56, v38
	v_fma_f32 v57, v43, v57, v39
	v_fma_f32 v58, v44, v58, v40
	v_fma_f32 v59, v45, v59, v41
	v_fma_f32 v60, v46, v60, v50
	v_fma_f32 v61, v47, v61, v51
	v_fma_f32 v62, v48, v62, v52
	v_fma_f32 v63, v49, v63, v53
	v_cvt_pk_bf16_f32 v64, v56, v57
	v_cvt_pk_bf16_f32 v65, v58, v59
	v_cvt_pk_bf16_f32 v66, v60, v61
	v_cvt_pk_bf16_f32 v67, v62, v63
	ds_write_b128 v212, v[64:67]
	ds_write_b128 v213, v[16:19]
	s_waitcnt lgkmcnt(4)
	v_lshlrev_b32_e32 v56, 16, v4
	v_and_b32_e32 v57, 0xffff0000, v4
	v_lshlrev_b32_e32 v58, 16, v5
	v_and_b32_e32 v59, 0xffff0000, v5
	v_lshlrev_b32_e32 v60, 16, v6
	v_and_b32_e32 v61, 0xffff0000, v6
	v_lshlrev_b32_e32 v62, 16, v7
	v_and_b32_e32 v63, 0xffff0000, v7
	v_sub_f32_e32 v56, v56, v90
	v_sub_f32_e32 v57, v57, v90
	v_sub_f32_e32 v58, v58, v90
	v_sub_f32_e32 v59, v59, v90
	v_sub_f32_e32 v60, v60, v90
	v_sub_f32_e32 v61, v61, v90
	v_sub_f32_e32 v62, v62, v90
	v_sub_f32_e32 v63, v63, v90
	v_mul_f32_e32 v56, v91, v56
	v_mul_f32_e32 v57, v91, v57
	v_mul_f32_e32 v58, v91, v58
	v_mul_f32_e32 v59, v91, v59
	v_mul_f32_e32 v60, v91, v60
	v_mul_f32_e32 v61, v91, v61
	v_mul_f32_e32 v62, v91, v62
	v_mul_f32_e32 v63, v91, v63
	v_fma_f32 v56, v42, v56, v38
	v_fma_f32 v57, v43, v57, v39
	v_fma_f32 v58, v44, v58, v40
	v_fma_f32 v59, v45, v59, v41
	v_fma_f32 v60, v46, v60, v50
	v_fma_f32 v61, v47, v61, v51
	v_fma_f32 v62, v48, v62, v52
	v_fma_f32 v63, v49, v63, v53
	v_cvt_pk_bf16_f32 v64, v56, v57
	v_cvt_pk_bf16_f32 v65, v58, v59
	v_cvt_pk_bf16_f32 v66, v60, v61
	v_cvt_pk_bf16_f32 v67, v62, v63
	ds_write_b128 v212, v[64:67] offset:9216
	ds_write_b128 v213, v[20:23] offset:8704
	s_waitcnt lgkmcnt(5)
	v_lshlrev_b32_e32 v56, 16, v8
	v_and_b32_e32 v57, 0xffff0000, v8
	v_lshlrev_b32_e32 v58, 16, v9
	v_and_b32_e32 v59, 0xffff0000, v9
	v_lshlrev_b32_e32 v60, 16, v10
	v_and_b32_e32 v61, 0xffff0000, v10
	v_lshlrev_b32_e32 v62, 16, v11
	v_and_b32_e32 v63, 0xffff0000, v11
	v_sub_f32_e32 v56, v56, v92
	v_sub_f32_e32 v57, v57, v92
	v_sub_f32_e32 v58, v58, v92
	v_sub_f32_e32 v59, v59, v92
	v_sub_f32_e32 v60, v60, v92
	v_sub_f32_e32 v61, v61, v92
	v_sub_f32_e32 v62, v62, v92
	v_sub_f32_e32 v63, v63, v92
	v_mul_f32_e32 v56, v93, v56
	v_mul_f32_e32 v57, v93, v57
	v_mul_f32_e32 v58, v93, v58
	v_mul_f32_e32 v59, v93, v59
	v_mul_f32_e32 v60, v93, v60
	v_mul_f32_e32 v61, v93, v61
	v_mul_f32_e32 v62, v93, v62
	v_mul_f32_e32 v63, v93, v63
	v_fma_f32 v56, v42, v56, v38
	v_fma_f32 v57, v43, v57, v39
	v_fma_f32 v58, v44, v58, v40
	v_fma_f32 v59, v45, v59, v41
	v_fma_f32 v60, v46, v60, v50
	v_fma_f32 v61, v47, v61, v51
	v_fma_f32 v62, v48, v62, v52
	v_fma_f32 v63, v49, v63, v53
	v_cvt_pk_bf16_f32 v64, v56, v57
	v_cvt_pk_bf16_f32 v65, v58, v59
	v_cvt_pk_bf16_f32 v66, v60, v61
	v_cvt_pk_bf16_f32 v67, v62, v63
	ds_write_b128 v212, v[64:67] offset:18432
	ds_write_b128 v213, v[24:27] offset:17408
	s_waitcnt lgkmcnt(6)
	v_lshlrev_b32_e32 v56, 16, v12
	v_and_b32_e32 v57, 0xffff0000, v12
	v_lshlrev_b32_e32 v58, 16, v13
	v_and_b32_e32 v59, 0xffff0000, v13
	v_lshlrev_b32_e32 v60, 16, v14
	v_and_b32_e32 v61, 0xffff0000, v14
	v_lshlrev_b32_e32 v62, 16, v15
	v_and_b32_e32 v63, 0xffff0000, v15
	v_sub_f32_e32 v56, v56, v94
	v_sub_f32_e32 v57, v57, v94
	v_sub_f32_e32 v58, v58, v94
	v_sub_f32_e32 v59, v59, v94
	v_sub_f32_e32 v60, v60, v94
	v_sub_f32_e32 v61, v61, v94
	v_sub_f32_e32 v62, v62, v94
	v_sub_f32_e32 v63, v63, v94
	v_mul_f32_e32 v56, v95, v56
	v_mul_f32_e32 v57, v95, v57
	v_mul_f32_e32 v58, v95, v58
	v_mul_f32_e32 v59, v95, v59
	v_mul_f32_e32 v60, v95, v60
	v_mul_f32_e32 v61, v95, v61
	v_mul_f32_e32 v62, v95, v62
	v_mul_f32_e32 v63, v95, v63
	v_fma_f32 v56, v42, v56, v38
	v_fma_f32 v57, v43, v57, v39
	v_fma_f32 v58, v44, v58, v40
	v_fma_f32 v59, v45, v59, v41
	v_fma_f32 v60, v46, v60, v50
	v_fma_f32 v61, v47, v61, v51
	v_fma_f32 v62, v48, v62, v52
	v_fma_f32 v63, v49, v63, v53
	v_cvt_pk_bf16_f32 v64, v56, v57
	v_cvt_pk_bf16_f32 v65, v58, v59
	v_cvt_pk_bf16_f32 v66, v60, v61
	v_cvt_pk_bf16_f32 v67, v62, v63
	ds_write_b128 v212, v[64:67] offset:27648
	ds_write_b128 v213, v[28:31] offset:26112
	s_waitcnt lgkmcnt(0)
	s_barrier
	ds_read2_b64 v[12:15], v217 offset1:4
	ds_read2_b64 v[8:11], v217 offset0:8 offset1:12
	ds_read2_b64 v[0:3], v217 offset0:16 offset1:20
	ds_read2_b64 v[4:7], v217 offset0:24 offset1:28
	ds_read_b64_tr_b16 v[18:19], v216
	ds_read_b64_tr_b16 v[20:21], v216 offset:4608
	ds_read_b64_tr_b16 v[22:23], v216 offset:9216
	ds_read_b64_tr_b16 v[24:25], v216 offset:13824
	ds_read_b64_tr_b16 v[26:27], v216 offset:18432
	ds_read_b64_tr_b16 v[28:29], v216 offset:23040
	ds_read_b64_tr_b16 v[30:31], v216 offset:27648
	ds_read_b64_tr_b16 v[32:33], v216 offset:32256
	s_waitcnt lgkmcnt(0)
	ds_read_b64_tr_b16 v[54:55], v216 offset:32
	ds_read_b64_tr_b16 v[56:57], v216 offset:4640
	ds_read_b64_tr_b16 v[58:59], v216 offset:9248
	ds_read_b64_tr_b16 v[60:61], v216 offset:13856
	ds_read_b64_tr_b16 v[62:63], v216 offset:18464
	ds_read_b64_tr_b16 v[64:65], v216 offset:23072
	ds_read_b64_tr_b16 v[66:67], v216 offset:27680
	ds_read_b64_tr_b16 v[68:69], v216 offset:32288
	v_mfma_f32_16x16x32_bf16 v[34:37], v[18:21], v[12:15], 0
	v_mfma_f32_16x16x32_bf16 v[34:37], v[22:25], v[8:11], v[34:37]
	v_mfma_f32_16x16x32_bf16 v[34:37], v[26:29], v[0:3], v[34:37]
	v_mfma_f32_16x16x32_bf16 v[34:37], v[30:33], v[4:7], v[34:37]
	s_waitcnt lgkmcnt(0)
	ds_read_b64_tr_b16 v[18:19], v216 offset:64
	ds_read_b64_tr_b16 v[20:21], v216 offset:4672
	ds_read_b64_tr_b16 v[22:23], v216 offset:9280
	ds_read_b64_tr_b16 v[24:25], v216 offset:13888
	ds_read_b64_tr_b16 v[26:27], v216 offset:18496
	ds_read_b64_tr_b16 v[28:29], v216 offset:23104
	ds_read_b64_tr_b16 v[30:31], v216 offset:27712
	ds_read_b64_tr_b16 v[32:33], v216 offset:32320
	v_mfma_f32_16x16x32_bf16 v[88:91], v[54:57], v[12:15], 0
	v_lshlrev_b32_e32 v38, 16, v70
	v_and_b32_e32 v39, 0xffff0000, v70
	v_lshlrev_b32_e32 v40, 16, v71
	v_and_b32_e32 v41, 0xffff0000, v71
	v_mfma_f32_16x16x32_bf16 v[88:91], v[58:61], v[8:11], v[88:91]
	v_add_f32_e32 v42, v86, v34
	v_add_f32_e32 v43, v86, v35
	v_add_f32_e32 v44, v86, v36
	v_add_f32_e32 v45, v86, v37
	v_mfma_f32_16x16x32_bf16 v[88:91], v[62:65], v[0:3], v[88:91]
	v_mul_f32_e32 v42, v42, v38
	v_mul_f32_e32 v43, v43, v39
	v_mul_f32_e32 v44, v44, v40
	v_mul_f32_e32 v45, v45, v41
	v_mfma_f32_16x16x32_bf16 v[88:91], v[66:69], v[4:7], v[88:91]
	v_cvt_pk_bf16_f32 v48, v42, v43
	v_cvt_pk_bf16_f32 v49, v44, v45
	s_waitcnt lgkmcnt(0)
	ds_read_b64_tr_b16 v[54:55], v216 offset:96
	ds_read_b64_tr_b16 v[56:57], v216 offset:4704
	ds_read_b64_tr_b16 v[58:59], v216 offset:9312
	ds_read_b64_tr_b16 v[60:61], v216 offset:13920
	ds_read_b64_tr_b16 v[62:63], v216 offset:18528
	ds_read_b64_tr_b16 v[64:65], v216 offset:23136
	ds_read_b64_tr_b16 v[66:67], v216 offset:27744
	ds_read_b64_tr_b16 v[68:69], v216 offset:32352
	v_mfma_f32_16x16x32_bf16 v[34:37], v[18:21], v[12:15], 0
	v_lshlrev_b32_e32 v38, 16, v72
	v_and_b32_e32 v39, 0xffff0000, v72
	v_lshlrev_b32_e32 v40, 16, v73
	v_and_b32_e32 v41, 0xffff0000, v73
	v_mfma_f32_16x16x32_bf16 v[34:37], v[22:25], v[8:11], v[34:37]
	v_add_f32_e32 v42, v86, v88
	v_add_f32_e32 v43, v86, v89
	v_add_f32_e32 v44, v86, v90
	v_add_f32_e32 v45, v86, v91
	v_mfma_f32_16x16x32_bf16 v[34:37], v[26:29], v[0:3], v[34:37]
	v_mul_f32_e32 v42, v42, v38
	v_mul_f32_e32 v43, v43, v39
	v_mul_f32_e32 v44, v44, v40
	v_mul_f32_e32 v45, v45, v41
	v_mfma_f32_16x16x32_bf16 v[34:37], v[30:33], v[4:7], v[34:37]
	v_cvt_pk_bf16_f32 v50, v42, v43
	v_cvt_pk_bf16_f32 v51, v44, v45
	s_nop 1
	v_permlane16_swap_b32 v48, v50
	v_permlane16_swap_b32 v49, v51
	global_store_dwordx4 v218, v[48:51], s[12:13]
	s_waitcnt lgkmcnt(0)
	ds_read_b64_tr_b16 v[18:19], v216 offset:128
	ds_read_b64_tr_b16 v[20:21], v216 offset:4736
	ds_read_b64_tr_b16 v[22:23], v216 offset:9344
	ds_read_b64_tr_b16 v[24:25], v216 offset:13952
	ds_read_b64_tr_b16 v[26:27], v216 offset:18560
	ds_read_b64_tr_b16 v[28:29], v216 offset:23168
	ds_read_b64_tr_b16 v[30:31], v216 offset:27776
	ds_read_b64_tr_b16 v[32:33], v216 offset:32384
	v_mfma_f32_16x16x32_bf16 v[88:91], v[54:57], v[12:15], 0
	v_lshlrev_b32_e32 v38, 16, v74
	v_and_b32_e32 v39, 0xffff0000, v74
	v_lshlrev_b32_e32 v40, 16, v75
	v_and_b32_e32 v41, 0xffff0000, v75
	v_mfma_f32_16x16x32_bf16 v[88:91], v[58:61], v[8:11], v[88:91]
	v_add_f32_e32 v42, v86, v34
	v_add_f32_e32 v43, v86, v35
	v_add_f32_e32 v44, v86, v36
	v_add_f32_e32 v45, v86, v37
	v_mfma_f32_16x16x32_bf16 v[88:91], v[62:65], v[0:3], v[88:91]
	v_mul_f32_e32 v42, v42, v38
	v_mul_f32_e32 v43, v43, v39
	v_mul_f32_e32 v44, v44, v40
	v_mul_f32_e32 v45, v45, v41
	v_mfma_f32_16x16x32_bf16 v[88:91], v[66:69], v[4:7], v[88:91]
	v_cvt_pk_bf16_f32 v48, v42, v43
	v_cvt_pk_bf16_f32 v49, v44, v45
	s_waitcnt lgkmcnt(0)
	ds_read_b64_tr_b16 v[54:55], v216 offset:160
	ds_read_b64_tr_b16 v[56:57], v216 offset:4768
	ds_read_b64_tr_b16 v[58:59], v216 offset:9376
	ds_read_b64_tr_b16 v[60:61], v216 offset:13984
	ds_read_b64_tr_b16 v[62:63], v216 offset:18592
	ds_read_b64_tr_b16 v[64:65], v216 offset:23200
	ds_read_b64_tr_b16 v[66:67], v216 offset:27808
	ds_read_b64_tr_b16 v[68:69], v216 offset:32416
	v_mfma_f32_16x16x32_bf16 v[34:37], v[18:21], v[12:15], 0
	v_lshlrev_b32_e32 v38, 16, v76
	v_and_b32_e32 v39, 0xffff0000, v76
	v_lshlrev_b32_e32 v40, 16, v77
	v_and_b32_e32 v41, 0xffff0000, v77
	v_mfma_f32_16x16x32_bf16 v[34:37], v[22:25], v[8:11], v[34:37]
	v_add_f32_e32 v42, v86, v88
	v_add_f32_e32 v43, v86, v89
	v_add_f32_e32 v44, v86, v90
	v_add_f32_e32 v45, v86, v91
	v_mfma_f32_16x16x32_bf16 v[34:37], v[26:29], v[0:3], v[34:37]
	v_mul_f32_e32 v42, v42, v38
	v_mul_f32_e32 v43, v43, v39
	v_mul_f32_e32 v44, v44, v40
	v_mul_f32_e32 v45, v45, v41
	v_mfma_f32_16x16x32_bf16 v[34:37], v[30:33], v[4:7], v[34:37]
	v_cvt_pk_bf16_f32 v50, v42, v43
	v_cvt_pk_bf16_f32 v51, v44, v45
	s_nop 1
	v_permlane16_swap_b32 v48, v50
	v_permlane16_swap_b32 v49, v51
	global_store_dwordx4 v218, v[48:51], s[12:13] offset:64
	s_waitcnt lgkmcnt(0)
	ds_read_b64_tr_b16 v[18:19], v216 offset:192
	ds_read_b64_tr_b16 v[20:21], v216 offset:4800
	ds_read_b64_tr_b16 v[22:23], v216 offset:9408
	ds_read_b64_tr_b16 v[24:25], v216 offset:14016
	ds_read_b64_tr_b16 v[26:27], v216 offset:18624
	ds_read_b64_tr_b16 v[28:29], v216 offset:23232
	ds_read_b64_tr_b16 v[30:31], v216 offset:27840
	ds_read_b64_tr_b16 v[32:33], v216 offset:32448
	v_mfma_f32_16x16x32_bf16 v[88:91], v[54:57], v[12:15], 0
	v_lshlrev_b32_e32 v38, 16, v78
	v_and_b32_e32 v39, 0xffff0000, v78
	v_lshlrev_b32_e32 v40, 16, v79
	v_and_b32_e32 v41, 0xffff0000, v79
	v_mfma_f32_16x16x32_bf16 v[88:91], v[58:61], v[8:11], v[88:91]
	v_add_f32_e32 v42, v86, v34
	v_add_f32_e32 v43, v86, v35
	v_add_f32_e32 v44, v86, v36
	v_add_f32_e32 v45, v86, v37
	v_mfma_f32_16x16x32_bf16 v[88:91], v[62:65], v[0:3], v[88:91]
	v_mul_f32_e32 v42, v42, v38
	v_mul_f32_e32 v43, v43, v39
	v_mul_f32_e32 v44, v44, v40
	v_mul_f32_e32 v45, v45, v41
	v_mfma_f32_16x16x32_bf16 v[88:91], v[66:69], v[4:7], v[88:91]
	v_cvt_pk_bf16_f32 v48, v42, v43
	v_cvt_pk_bf16_f32 v49, v44, v45
	s_waitcnt lgkmcnt(0)
	ds_read_b64_tr_b16 v[54:55], v216 offset:224
	ds_read_b64_tr_b16 v[56:57], v216 offset:4832
	ds_read_b64_tr_b16 v[58:59], v216 offset:9440
	ds_read_b64_tr_b16 v[60:61], v216 offset:14048
	ds_read_b64_tr_b16 v[62:63], v216 offset:18656
	ds_read_b64_tr_b16 v[64:65], v216 offset:23264
	ds_read_b64_tr_b16 v[66:67], v216 offset:27872
	ds_read_b64_tr_b16 v[68:69], v216 offset:32480
	v_mfma_f32_16x16x32_bf16 v[34:37], v[18:21], v[12:15], 0
	v_lshlrev_b32_e32 v38, 16, v80
	v_and_b32_e32 v39, 0xffff0000, v80
	v_lshlrev_b32_e32 v40, 16, v81
	v_and_b32_e32 v41, 0xffff0000, v81
	v_mfma_f32_16x16x32_bf16 v[34:37], v[22:25], v[8:11], v[34:37]
	v_add_f32_e32 v42, v86, v88
	v_add_f32_e32 v43, v86, v89
	v_add_f32_e32 v44, v86, v90
	v_add_f32_e32 v45, v86, v91
	v_mfma_f32_16x16x32_bf16 v[34:37], v[26:29], v[0:3], v[34:37]
	v_mul_f32_e32 v42, v42, v38
	v_mul_f32_e32 v43, v43, v39
	v_mul_f32_e32 v44, v44, v40
	v_mul_f32_e32 v45, v45, v41
	v_mfma_f32_16x16x32_bf16 v[34:37], v[30:33], v[4:7], v[34:37]
	v_cvt_pk_bf16_f32 v50, v42, v43
	v_cvt_pk_bf16_f32 v51, v44, v45
	s_nop 1
	v_permlane16_swap_b32 v48, v50
	v_permlane16_swap_b32 v49, v51
	global_store_dwordx4 v218, v[48:51], s[12:13] offset:128
	s_waitcnt lgkmcnt(0)
	v_mfma_f32_16x16x32_bf16 v[88:91], v[54:57], v[12:15], 0
	v_lshlrev_b32_e32 v38, 16, v82
	v_and_b32_e32 v39, 0xffff0000, v82
	v_lshlrev_b32_e32 v40, 16, v83
	v_and_b32_e32 v41, 0xffff0000, v83
	v_mfma_f32_16x16x32_bf16 v[88:91], v[58:61], v[8:11], v[88:91]
	v_add_f32_e32 v42, v86, v34
	v_add_f32_e32 v43, v86, v35
	v_add_f32_e32 v44, v86, v36
	v_add_f32_e32 v45, v86, v37
	v_mfma_f32_16x16x32_bf16 v[88:91], v[62:65], v[0:3], v[88:91]
	v_mul_f32_e32 v42, v42, v38
	v_mul_f32_e32 v43, v43, v39
	v_mul_f32_e32 v44, v44, v40
	v_mul_f32_e32 v45, v45, v41
	v_mfma_f32_16x16x32_bf16 v[88:91], v[66:69], v[4:7], v[88:91]
	v_cvt_pk_bf16_f32 v48, v42, v43
	v_cvt_pk_bf16_f32 v49, v44, v45
	v_lshlrev_b32_e32 v38, 16, v84
	v_and_b32_e32 v39, 0xffff0000, v84
	v_lshlrev_b32_e32 v40, 16, v85
	v_and_b32_e32 v41, 0xffff0000, v85
	s_nop 3
	v_add_f32_e32 v42, v86, v88
	v_add_f32_e32 v43, v86, v89
	v_add_f32_e32 v44, v86, v90
	v_add_f32_e32 v45, v86, v91
	v_mul_f32_e32 v42, v42, v38
	v_mul_f32_e32 v43, v43, v39
	v_mul_f32_e32 v44, v44, v40
	v_mul_f32_e32 v45, v45, v41
	v_cvt_pk_bf16_f32 v50, v42, v43
	v_cvt_pk_bf16_f32 v51, v44, v45
	s_nop 1
	v_permlane16_swap_b32 v48, v50
	v_permlane16_swap_b32 v49, v51
	global_store_dwordx4 v218, v[48:51], s[12:13] offset:192
	s_add_i32 s5, s5, 1
	s_add_i32 s3, s3, -1
	s_cmp_gt_u32 s3, 0
	s_cbranch_scc1 .Lcmb_top

.LBB0_947:
	s_or_b64 exec, exec, s[0:1]
	s_waitcnt vmcnt(1)
	v_mov_b32_e32 v1, v195
	s_cmpk_lt_i32 s2, 0x200
	s_waitcnt lgkmcnt(0)
	s_barrier
	s_nop 0
	s_nop 0
	s_nop 0
	s_nop 0
	s_nop 0
	s_nop 0
	s_nop 0
	s_nop 0
	s_nop 0
	s_nop 0
	s_nop 0
	s_nop 0
	s_nop 0
	s_nop 0
	s_nop 0
	s_nop 0
	s_nop 0
	s_nop 0
	s_nop 0
	s_nop 0
	s_nop 0
	s_cselect_b64 s[4:5], -1, 0
	s_cmpk_gt_i32 s2, 0x1ff
	v_readfirstlane_b32 s3, v1
	s_cbranch_scc1 .LBB0_950
	s_and_b32 s8, s2, 7
	s_bfe_u32 s1, s2, 0x50003
	s_cmpk_gt_i32 s2, 0xff
	s_cbranch_scc0 .LBB0_951
	s_lshl_b32 s0, s8, 1
	s_bfe_u32 s6, s2, 0x10003
	s_or_b32 s0, s0, s6
	s_lshr_b32 s73, s1, 3
	s_or_b32 s0, s0, 64
	s_bfe_u32 s38, s2, 0x20004
	s_cmp_gt_u32 s1, 15
	s_cselect_b32 s6, 0x2800000, 0
	s_lshl_b32 s12, s73, 10
	s_mov_b32 s11, 0
	s_and_b32 s7, s12, 0x400
	s_or_b32 s10, s6, s7
	s_mov_b32 s13, s11
	s_mov_b32 s74, 8
	s_cbranch_execz .LBB0_952
	s_branch .LBB0_953
